# retention: on weight-conversion tiles issue next tile's K/V DMAs first at the tile top, keep the 8 f32 weight loads in flight across the tile end (vmcnt(8)), convert+store one tile later
# speedup vs baseline: 1.0009x; 1.0009x over previous
; #define RT_BAR() do { asm volatile("s_waitcnt lgkmcnt(0)" ::: "memory"); __builtin_amdgcn_s_barrier(); asm volatile("" ::: "memory"); } while (0)
; __device__ __forceinline__ void p2_ret(const Frame& F, ArgsP a, int layer) {
;     ...
;             const int qi = uu ? p : 15 - p, ntile = 2 * (qi + 1);
;             const size_t tokq = (size_t)b * SEQ + qi * 128;
;             f32x16 oacc[4];
; #pragma unroll
;             for (int db = 0; db < 4; ++db)
; #pragma unroll
;                 for (int r = 0; r < 16; ++r) oacc[db][r] = 0.f;
;             asm volatile("s_waitcnt vmcnt(0)" ::: "memory"); RT_BAR();
.LBB0_355:
	s_xor_b64 s[72:73], s[74:75], -1
	s_and_b64 s[2:3], s[74:75], exec
	s_waitcnt vmcnt(0)
	s_cselect_b32 s96, s89, s50
	s_waitcnt lgkmcnt(0)
	s_barrier
	v_writelane_b32 v255, 0, 63
	s_nop 0
	s_lshl_b32 s19, s96, 7
	s_lshl_b32 s11, s96, 8
	v_mov_b32_e32 v34, 0
	s_lshl_b32 s29, s96, 1
	s_add_i32 s97, s81, s19
	s_bitset1_b32 s11, 7
	s_mov_b32 s31, 0
	s_mov_b32 s27, s88
	s_mov_b32 s30, 0
	s_mov_b32 s91, 0
	v_mov_b32_e32 v35, v34
	v_mov_b32_e32 v36, v34
	v_mov_b32_e32 v37, v34
	v_mov_b32_e32 v38, v34
	v_mov_b32_e32 v39, v34
	v_mov_b32_e32 v40, v34
	v_mov_b32_e32 v41, v34
	v_mov_b32_e32 v42, v34
	v_mov_b32_e32 v43, v34
	v_mov_b32_e32 v44, v34
	v_mov_b32_e32 v45, v34
	v_mov_b32_e32 v46, v34
	v_mov_b32_e32 v47, v34
	v_mov_b32_e32 v48, v34
	v_mov_b32_e32 v49, v34
	v_mov_b32_e32 v50, v34
	v_mov_b32_e32 v51, v34
	v_mov_b32_e32 v52, v34
	v_mov_b32_e32 v53, v34
	v_mov_b32_e32 v54, v34
	v_mov_b32_e32 v55, v34
	v_mov_b32_e32 v56, v34
	v_mov_b32_e32 v57, v34
	v_mov_b32_e32 v58, v34
	v_mov_b32_e32 v59, v34
	v_mov_b32_e32 v60, v34
	v_mov_b32_e32 v61, v34
	v_mov_b32_e32 v62, v34
	v_mov_b32_e32 v63, v34
	v_mov_b32_e32 v64, v34
	v_mov_b32_e32 v65, v34
	v_mov_b32_e32 v66, v34
	v_mov_b32_e32 v67, v34
	v_mov_b32_e32 v68, v34
	v_mov_b32_e32 v69, v34
	v_mov_b32_e32 v70, v34
	v_mov_b32_e32 v71, v34
	v_mov_b32_e32 v72, v34
	v_mov_b32_e32 v73, v34
	v_mov_b32_e32 v74, v34
	v_mov_b32_e32 v75, v34
	v_mov_b32_e32 v76, v34
	v_mov_b32_e32 v77, v34
	v_mov_b32_e32 v78, v34
	v_mov_b32_e32 v79, v34
	v_mov_b32_e32 v80, v34
	v_mov_b32_e32 v81, v34
	v_mov_b32_e32 v82, v34
	v_mov_b32_e32 v83, v34
	v_mov_b32_e32 v84, v34
	v_mov_b32_e32 v85, v34
	v_mov_b32_e32 v86, v34
	v_mov_b32_e32 v87, v34
	v_mov_b32_e32 v88, v34
	v_mov_b32_e32 v89, v34
	v_mov_b32_e32 v90, v34
	v_mov_b32_e32 v91, v34
	v_mov_b32_e32 v92, v34
	v_mov_b32_e32 v93, v34
	v_mov_b32_e32 v94, v34
	v_mov_b32_e32 v95, v34
	v_mov_b32_e32 v96, v34
	v_mov_b32_e32 v97, v34
	s_branch .LBB0_358

; #define LAS __attribute__((address_space(3)))
; #define RT_DMA_K(kt_, bf_, i_) __builtin_amdgcn_raw_ptr_buffer_load_lds(RK, (LAS void*)(lds + RT_K0 + (bf_) * 32768 + (w + 8 * (i_)) * 1024), 16, (int)RT_KOFF, (int)((unsigned)((b * SEQ + (kt_) * 64) * DR + h * 256) * 2u + (i_) * 65536u), 0, 0)
; #define RT_DMA_V(kt_, bf_, i_) __builtin_amdgcn_raw_ptr_buffer_load_lds(RV, (LAS void*)(lds + RT_V0 + (bf_) * 32768 + (w + 8 * (i_)) * 1024), 16, (int)RT_VOFF, (int)((unsigned)((h * 256) * MTOK + b * SEQ + (kt_) * 64) * 2u + (i_) * 1048576u), 0, 0)
; __device__ __forceinline__ void p2_ret(const Frame& F, ArgsP a, int layer) {
;     ...
;                 const bool cv = cvhi < CV_HALF_ITEMS && ((cvtile++ & 1) == 0); f32x4 cvv[8], cvsc[2];
;                 if (cv) { const CvU cu = cv_decode(a, F.ws, cvhi, layer); cv_load(cu, lane, cvv, cvsc); }
;                 const int bf = kt & 1; const bool pre = kt + 1 < ntile;
;                 int lo_ = lane; asm volatile("" : "+v"(lo_));
;                 const int l31 = lo_ & 31, hh = lo_ >> 5, lane = lo_;
;                 const int kap = (l31 & 0x13) | ((l31 & 4) << 1) | ((l31 & 8) >> 1), x15 = kap & 15, m4 = ((kap >> 1) & 7) << 4;
;                 f32x16 st;
; #pragma unroll
;                 for (int r = 0; r < 16; ++r) st[r] = 0.f;
;                 { const LAS unsigned char* kb = lds + RT_K0 + bf * 32768 + (32 * wc + kap) * 512;
;     ...
;                   bf16x8 ka[2], kd[2], kc[2];
;                   RT_KRD(ka, 0); RT_KRD(kd, 2); __builtin_amdgcn_sched_barrier(0);
;                   RT_KRD(kc, 4); RT_KMM(ka, 0); if (pre) { RT_DMA_K(kt + 1, bf ^ 1, 0); RT_DMA_V(kt + 1, bf ^ 1, 0); } __builtin_amdgcn_sched_barrier(0);
;                   RT_KRD(ka, 6); RT_KMM(kd, 2); __builtin_amdgcn_sched_barrier(0);
;                   RT_KRD(kd, 8); RT_KMM(kc, 4); if (pre) { RT_DMA_K(kt + 1, bf ^ 1, 1); RT_DMA_V(kt + 1, bf ^ 1, 1); } __builtin_amdgcn_sched_barrier(0);
;                   RT_KRD(kc, 10); RT_KMM(ka, 6); __builtin_amdgcn_sched_barrier(0);
;                   RT_KRD(ka, 12); RT_KMM(kd, 8); if (pre) { RT_DMA_K(kt + 1, bf ^ 1, 2); RT_DMA_V(kt + 1, bf ^ 1, 2); } __builtin_amdgcn_sched_barrier(0);
;                   RT_KRD(kd, 14); RT_KMM(kc, 10); __builtin_amdgcn_sched_barrier(0);
;                   RT_KMM(ka, 12); if (pre) { RT_DMA_K(kt + 1, bf ^ 1, 3); RT_DMA_V(kt + 1, bf ^ 1, 3); } __builtin_amdgcn_sched_barrier(0);
.LBB0_358:
	s_cmp_lt_i32 s36, s93
	s_cselect_b64 s[2:3], -1, 0
	s_bitcmp0_b32 s37, 0
	s_cselect_b64 s[4:5], -1, 0
	s_and_b64 s[4:5], s[2:3], s[4:5]
	v_cndmask_b32_e64 v0, 0, 1, s[4:5]
	v_cmp_ne_u32_e64 s[38:39], 1, v0
	s_andn2_b64 vcc, exec, s[4:5]
	s_cbranch_vccnz .LBB0_383
	s_and_b32 s6, s31, 0x8000
	s_xor_b32 s4, s6, 0x8000
	s_add_i32 s5, s22, s4
	s_add_i32 s7, s27, 0xfffd0000
	s_mov_b32 m0, s5
	s_mov_b32 s46, s42
	s_mov_b32 s47, s43
	buffer_load_dwordx4 v224, s[40:43], s7 offen lds
	s_add_i32 m0, s5, 0x2000
	s_add_i32 s12, s27, 0xfffe0000
	buffer_load_dwordx4 v224, s[40:43], s12 offen lds
	s_add_i32 m0, s5, 0x4000
	s_add_i32 s12, s27, 0xffff0000
	buffer_load_dwordx4 v224, s[40:43], s12 offen lds
	s_add_i32 m0, s5, 0x6000
	s_nop 0
	buffer_load_dwordx4 v224, s[40:43], s27 offen lds
	s_add_i32 s7, s25, s30
	s_add_i32 m0, s33, s4
	s_add_i32 s12, s7, 0x80
	buffer_load_dwordx4 v225, s[44:47], s12 offen lds
	s_add_i32 s4, s4, 0x10000
	s_add_i32 m0, s4, s24
	s_add_i32 s12, s7, 0x100080
	buffer_load_dwordx4 v225, s[44:47], s12 offen lds
	s_add_i32 m0, s4, s26
	s_add_i32 s12, s7, 0x200080
	buffer_load_dwordx4 v225, s[44:47], s12 offen lds
	s_add_i32 m0, s4, s28
	s_add_i32 s12, s7, 0x300080
	buffer_load_dwordx4 v225, s[44:47], s12 offen lds
	s_ashr_i32 s15, s36, 1
	s_cmpk_gt_i32 s15, 0x3ff
	s_cselect_b64 s[6:7], -1, 0
	s_cmpk_lt_i32 s15, 0x400
	s_mov_b64 s[70:71], 0
	s_cbranch_scc1 .LBB0_365
	s_mov_b64 s[4:5], -1
	s_cmpk_gt_u32 s15, 0x13ff
	s_mov_b64 s[12:13], -1
	s_cbranch_scc0 .LBB0_362
	s_add_i32 s14, s15, 0xffffec00
	s_mov_b64 s[12:13], 0

; __device__ __forceinline__ void cv_load(const CvU& u, int lane, f32x4 (&v)[8], f32x4 (&sc)[2]) {
;     const int nq = lane & 15, kq = lane >> 4;
;     const float* wp = u.W + (size_t)(u.k0 + 8 * kq) * u.N + u.n0 + 4 * nq;
; #pragma unroll
;     for (int i = 0; i < 8; ++i) v[i] = __builtin_nontemporal_load((const f32x4*)(wp + (size_t)i * u.N));
;     if (u.ks) { sc[0] = *(const f32x4*)(u.ks + 8 * kq); sc[1] = *(const f32x4*)(u.ks + 8 * kq + 4); }
;     else { sc[0] = (f32x4){1.f, 1.f, 1.f, 1.f}; sc[1] = sc[0]; }
.LBB0_380:
	s_cmp_eq_u64 s[70:71], 0
	s_cbranch_scc1 .Lrt_noscale
	v_lshlrev_b32_e32 v0, 2, v206
	global_load_dwordx4 v[182:185], v0, s[70:71] offset:16
	global_load_dwordx4 v[186:189], v0, s[70:71]
	s_branch .Lrt_wload

; __device__ __forceinline__ void cv_load(const CvU& u, int lane, f32x4 (&v)[8], f32x4 (&sc)[2]) {
;     const int nq = lane & 15, kq = lane >> 4;
;     const float* wp = u.W + (size_t)(u.k0 + 8 * kq) * u.N + u.n0 + 4 * nq;
; #pragma unroll
;     for (int i = 0; i < 8; ++i) v[i] = __builtin_nontemporal_load((const f32x4*)(wp + (size_t)i * u.N));
.Lrt_wload:
	v_or_b32_e32 v0, s6, v206
	s_ashr_i32 s5, s6, 31
	v_mul_lo_u32 v4, s77, v0
	s_mul_i32 s5, s76, s5
	v_mad_u64_u32 v[2:3], s[6:7], s76, v0, 0
	s_lshl_b32 s4, s14, 6
	v_add3_u32 v3, v3, s5, v4
	v_lshl_add_u64 v[2:3], v[2:3], 2, s[46:47]
	s_ashr_i32 s5, s4, 31
	v_lshl_add_u64 v[2:3], s[4:5], 2, v[2:3]
	v_lshlrev_b32_e32 v0, 2, v208
	v_lshl_add_u64 v[2:3], v[2:3], 0, v[0:1]
	s_lshl_b64 s[4:5], s[76:77], 2
	v_lshl_add_u64 v[10:11], v[2:3], 0, s[4:5]
	global_load_dwordx4 v[2:5], v[2:3], off nt
	s_nop 0
	global_load_dwordx4 v[6:9], v[10:11], off nt
	v_lshl_add_u64 v[10:11], v[10:11], 0, s[4:5]
	v_lshl_add_u64 v[18:19], v[10:11], 0, s[4:5]
	global_load_dwordx4 v[10:13], v[10:11], off nt
	s_nop 0
	global_load_dwordx4 v[14:17], v[18:19], off nt
	v_lshl_add_u64 v[18:19], v[18:19], 0, s[4:5]
	v_lshl_add_u64 v[26:27], v[18:19], 0, s[4:5]
	global_load_dwordx4 v[18:21], v[18:19], off nt
	s_nop 0
	global_load_dwordx4 v[22:25], v[26:27], off nt
	v_lshl_add_u64 v[26:27], v[26:27], 0, s[4:5]
	v_lshl_add_u64 v[30:31], v[26:27], 0, s[4:5]
	global_load_dwordx4 v[26:29], v[26:27], off nt
	s_nop 0
	global_load_dwordx4 v[30:33], v[30:31], off nt
	s_branch .Lrt_sB

; __device__ __forceinline__ unsigned cvt_pk_bf16(float lo, float hi) { unsigned r; asm volatile("v_cvt_pk_bf16_f32 %0, %1, %2" : "=v"(r) : "v"(lo), "v"(hi)); return r; }
; __device__ __forceinline__ void p2_ret(const Frame& F, ArgsP a, int layer) {
;     ...
;                 { const bool diag = kt >= 2 * qi;
;                   unsigned pk[8];
;                   if (!diag) { const float tf = __builtin_amdgcn_exp2f((float)(128 * (qi - (kt >> 1))) * lg2);
; #pragma unroll
;                       for (int i = 0; i < 8; ++i) pk[i] = cvt_pk_bf16(st[2 * i] * tf, st[2 * i + 1] * tf);
;                   } else { const int lim = wr * 32 + l31 + (2 * qi - kt) * 64 - 32 * wc - 8 * hh;
; #pragma unroll
;                       for (int i = 0; i < 8; ++i) { const int r0 = 2 * i, r1 = 2 * i + 1, o0 = 16 * (r0 >> 3) + (r0 & 7), o1 = 16 * (r1 >> 3) + (r1 & 7);
;                           pk[i] = cvt_pk_bf16((o0 <= lim) ? st[r0] : 0.f, (o1 <= lim) ? st[r1] : 0.f); } }
.Lrt_join:
	s_cmp_ge_u32 s91, s29
	s_mov_b64 s[4:5], -1
	s_cbranch_scc0 .LBB0_385
	v_lshlrev_b32_e32 v190, 3, v116
	v_sub_u32_e32 v117, v117, v190
	v_add_u32_e32 v117, s97, v117
	v_cmp_lt_i32_e32 vcc, -1, v117
	s_mov_b64 s[4:5], 0
	s_nop 3
	v_cndmask_b32_e32 v190, 0, v98, vcc
	v_cmp_lt_i32_e32 vcc, 0, v117
	s_nop 1
	v_cndmask_b32_e32 v191, 0, v99, vcc
	v_cmp_lt_i32_e32 vcc, 1, v117
	v_cvt_pk_bf16_f32 v190, v190, v191
	s_nop 1
	v_cndmask_b32_e32 v191, 0, v100, vcc
	v_cmp_lt_i32_e32 vcc, 2, v117
	s_nop 1
	v_cndmask_b32_e32 v192, 0, v101, vcc
	v_cmp_lt_i32_e32 vcc, 3, v117
	v_cvt_pk_bf16_f32 v191, v191, v192
	s_nop 1
	v_cndmask_b32_e32 v192, 0, v102, vcc
	v_cmp_lt_i32_e32 vcc, 4, v117
	s_nop 1
	v_cndmask_b32_e32 v193, 0, v103, vcc
	v_cmp_lt_i32_e32 vcc, 5, v117
	v_cvt_pk_bf16_f32 v192, v192, v193
	s_nop 1
	v_cndmask_b32_e32 v193, 0, v104, vcc
	v_cmp_lt_i32_e32 vcc, 6, v117
	s_nop 1
	v_cndmask_b32_e32 v194, 0, v105, vcc
	v_cmp_lt_i32_e32 vcc, 15, v117
	v_cvt_pk_bf16_f32 v193, v193, v194
	s_nop 1
	v_cndmask_b32_e32 v194, 0, v106, vcc
	v_cmp_lt_i32_e32 vcc, 16, v117
	s_nop 1
	v_cndmask_b32_e32 v195, 0, v107, vcc
	v_cmp_lt_i32_e32 vcc, 17, v117
	v_cvt_pk_bf16_f32 v194, v194, v195
	s_nop 1
	v_cndmask_b32_e32 v195, 0, v108, vcc
	v_cmp_lt_i32_e32 vcc, 18, v117
	s_nop 1
	v_cndmask_b32_e32 v196, 0, v109, vcc
	v_cmp_lt_i32_e32 vcc, 19, v117
	v_cvt_pk_bf16_f32 v195, v195, v196
	s_nop 1
	v_cndmask_b32_e32 v196, 0, v110, vcc
	v_cmp_lt_i32_e32 vcc, 20, v117
	s_nop 1
	v_cndmask_b32_e32 v197, 0, v111, vcc
	v_cmp_lt_i32_e32 vcc, 21, v117
	v_cvt_pk_bf16_f32 v196, v196, v197
	s_nop 1
	v_cndmask_b32_e32 v197, 0, v112, vcc
	v_cmp_lt_i32_e32 vcc, 22, v117
	s_nop 1
	v_cndmask_b32_e32 v117, 0, v113, vcc
	v_cvt_pk_bf16_f32 v197, v197, v117

; #define LAS __attribute__((address_space(3)))
; #define RT_BAR() do { asm volatile("s_waitcnt lgkmcnt(0)" ::: "memory"); __builtin_amdgcn_s_barrier(); asm volatile("" ::: "memory"); } while (0)
; #define RT_VRD(dst, g) do { _Pragma("unroll") for (int j_ = 0; j_ < 2; ++j_) { const int jj_ = 2 * ((g) & 1) + j_; dst[j_] = *(const LAS bf16x8*)(vb + ((g) >> 1) * 4096 + (((4 * (jj_ >> 1) + 2 * (jj_ & 1) + hh) << 4) ^ m4)); } } while (0)
; __device__ __forceinline__ void p2_ret(const Frame& F, ArgsP a, int layer) {
;     ...
;                   LAS unsigned char* pw = lds + RT_P + ((wr * 2 + wc) * 2) * 1024 + lane * 16;
;                   *(LAS u32x4*)pw = (u32x4){pk[0], pk[1], pk[2], pk[3]}; *(LAS u32x4*)(pw + 1024) = (u32x4){pk[4], pk[5], pk[6], pk[7]}; }
;                 RT_BAR();
;                 { bf16x8 pf[2][2];
; #pragma unroll
;                   for (int kb2 = 0; kb2 < 2; ++kb2)
; #pragma unroll
;                       for (int s = 0; s < 2; ++s) pf[kb2][s] = *(const LAS bf16x8*)(lds + RT_P + ((wr * 2 + kb2) * 2 + s) * 1024 + lane * 16);
;                   const LAS unsigned char* vb = lds + RT_V0 + bf * 32768 + (128 * wc + kap) * 128;
;     ...
;                   bf16x8 va[2], vc[2];
;                   RT_VRD(va, 0); __builtin_amdgcn_sched_barrier(0);
;                   RT_VRD(vc, 1); RT_VMM(va, 0); __builtin_amdgcn_sched_barrier(0);
;                   RT_VRD(va, 2); RT_VMM(vc, 1); __builtin_amdgcn_sched_barrier(0);
;                   RT_VRD(vc, 3); RT_VMM(va, 2); __builtin_amdgcn_sched_barrier(0);
;                   RT_VRD(va, 4); RT_VMM(vc, 3); __builtin_amdgcn_sched_barrier(0);
;                   RT_VRD(vc, 5); RT_VMM(va, 4); __builtin_amdgcn_sched_barrier(0);
;                   RT_VRD(va, 6); RT_VMM(vc, 5); __builtin_amdgcn_sched_barrier(0);
;                   RT_VRD(vc, 7); RT_VMM(va, 6); __builtin_amdgcn_sched_barrier(0);
;                   RT_VMM(vc, 7); __builtin_amdgcn_sched_barrier(0);
;     ...
;                 }
;                 asm volatile("s_waitcnt vmcnt(0)" ::: "memory");
;                 if (cv) { const CvU cu = cv_decode(a, F.ws, cvhi, layer); cv_store(cu, lane, cvv, cvsc); cvhi += cvs; }
;                 RT_BAR();
.LBB0_387:
	s_nop 6
	v_lshlrev_b32_e32 v98, 3, v115
	v_and_b32_e32 v117, 0x70, v98
	v_lshlrev_b32_e32 v98, 4, v0
	v_add_u32_e32 v99, s83, v98
	ds_write_b128 v99, v[190:193]
	ds_write_b128 v99, v[194:197] offset:1024
	s_waitcnt lgkmcnt(0)
	s_barrier
	v_add_u32_e32 v110, s82, v98
	s_add_i32 s4, s64, s6
	ds_read_b128 v[98:101], v110
	ds_read_b128 v[102:105], v110 offset:1024
	ds_read_b128 v[106:109], v110 offset:2048
	ds_read_b128 v[110:113], v110 offset:3072
	v_lshl_add_u32 v115, v115, 7, s4
	v_lshlrev_b32_e32 v116, 4, v116
	v_xad_u32 v202, v117, v116, v115
	v_add_u32_e32 v190, 32, v116
	v_xad_u32 v203, v117, v190, v115
	ds_read_b128 v[190:193], v202
	ds_read_b128 v[194:197], v203
	s_waitcnt lgkmcnt(1)
	v_mfma_f32_32x32x16_bf16 v[82:97], v[190:193], v[98:101], v[82:97]
	v_add_u32_e32 v190, 64, v116
	v_xad_u32 v204, v117, v190, v115
	v_add_u32_e32 v116, 0x60, v116
	v_xad_u32 v115, v117, v116, v115
	ds_read_b128 v[190:193], v204
	ds_read_b128 v[198:201], v115
	s_waitcnt lgkmcnt(2)
	v_mfma_f32_32x32x16_bf16 v[82:97], v[194:197], v[102:105], v[82:97]
	s_waitcnt lgkmcnt(1)
	v_mfma_f32_32x32x16_bf16 v[82:97], v[190:193], v[106:109], v[82:97]
	ds_read_b128 v[190:193], v202 offset:4096
	ds_read_b128 v[194:197], v203 offset:4096
	s_waitcnt lgkmcnt(2)
	v_mfma_f32_32x32x16_bf16 v[82:97], v[198:201], v[110:113], v[82:97]
	s_waitcnt lgkmcnt(1)
	v_mfma_f32_32x32x16_bf16 v[66:81], v[190:193], v[98:101], v[66:81]
	ds_read_b128 v[190:193], v204 offset:4096
	ds_read_b128 v[198:201], v115 offset:4096
	s_waitcnt lgkmcnt(2)
	v_mfma_f32_32x32x16_bf16 v[66:81], v[194:197], v[102:105], v[66:81]
	s_waitcnt lgkmcnt(1)
	v_mfma_f32_32x32x16_bf16 v[66:81], v[190:193], v[106:109], v[66:81]
	ds_read_b128 v[190:193], v202 offset:8192
	ds_read_b128 v[194:197], v203 offset:8192
	s_waitcnt lgkmcnt(2)
	v_mfma_f32_32x32x16_bf16 v[66:81], v[198:201], v[110:113], v[66:81]
	s_waitcnt lgkmcnt(1)
	v_mfma_f32_32x32x16_bf16 v[50:65], v[190:193], v[98:101], v[50:65]
	ds_read_b128 v[190:193], v204 offset:8192
	ds_read_b128 v[198:201], v115 offset:8192
	s_waitcnt lgkmcnt(2)
	v_mfma_f32_32x32x16_bf16 v[50:65], v[194:197], v[102:105], v[50:65]
	s_waitcnt lgkmcnt(1)
	v_mfma_f32_32x32x16_bf16 v[50:65], v[190:193], v[106:109], v[50:65]
	ds_read_b128 v[190:193], v202 offset:12288
	ds_read_b128 v[194:197], v203 offset:12288
	s_waitcnt lgkmcnt(2)
	v_mfma_f32_32x32x16_bf16 v[50:65], v[198:201], v[110:113], v[50:65]
	s_waitcnt lgkmcnt(1)
	v_mfma_f32_32x32x16_bf16 v[34:49], v[190:193], v[98:101], v[34:49]
	ds_read_b128 v[98:101], v204 offset:12288
	ds_read_b128 v[190:193], v115 offset:12288
	s_waitcnt lgkmcnt(2)
	v_mfma_f32_32x32x16_bf16 v[34:49], v[194:197], v[102:105], v[34:49]
	s_waitcnt lgkmcnt(1)
	v_mfma_f32_32x32x16_bf16 v[34:49], v[98:101], v[106:109], v[34:49]
	s_waitcnt lgkmcnt(0)
	v_mfma_f32_32x32x16_bf16 v[34:49], v[190:193], v[110:113], v[34:49]
	s_and_b64 vcc, exec, s[38:39]
	s_cbranch_vccnz .Lrt_notcv
	s_add_i32 s4, s30, 0x80
	s_cmp_eq_u32 s11, s4
	s_cbranch_scc1 .Lrt_cvlast
	s_waitcnt vmcnt(8)
	s_mov_b32 s4, 1
	s_nop 0
	v_writelane_b32 v255, s4, 63
	s_branch .LBB0_357
.Lrt_cvlast:
	s_waitcnt vmcnt(0)
	s_branch .Lrt_store
.Lrt_notcv:
	s_waitcnt vmcnt(0)
	v_readlane_b32 s4, v255, 63
	s_cmp_eq_u32 s4, 0
	s_cbranch_scc1 .LBB0_357
	v_writelane_b32 v255, 0, 63
.Lrt_store:
	s_ashr_i32 s14, s36, 1
	s_cmpk_lt_i32 s14, 0x400
	s_cselect_b64 s[4:5], -1, 0
	s_mov_b64 s[70:71], 0
	s_and_b64 vcc, exec, s[4:5]
	s_cbranch_vccnz .LBB0_394
	s_mov_b64 s[46:47], -1
	s_cmpk_gt_u32 s14, 0x13ff
	s_mov_b64 s[6:7], -1
	s_cbranch_scc0 .LBB0_391
	s_add_i32 s12, s14, 0xffffec00
	s_mov_b64 s[6:7], 0

; #define LAS __attribute__((address_space(3)))
; #define RT_DMA_K(kt_, bf_, i_) __builtin_amdgcn_raw_ptr_buffer_load_lds(RK, (LAS void*)(lds + RT_K0 + (bf_) * 32768 + (w + 8 * (i_)) * 1024), 16, (int)RT_KOFF, (int)((unsigned)((b * SEQ + (kt_) * 64) * DR + h * 256) * 2u + (i_) * 65536u), 0, 0)
; #define RT_DMA_V(kt_, bf_, i_) __builtin_amdgcn_raw_ptr_buffer_load_lds(RV, (LAS void*)(lds + RT_V0 + (bf_) * 32768 + (w + 8 * (i_)) * 1024), 16, (int)RT_VOFF, (int)((unsigned)((h * 256) * MTOK + b * SEQ + (kt_) * 64) * 2u + (i_) * 1048576u), 0, 0)
; #define RT_KRD(dst, s0) do { _Pragma("unroll") for (int j_ = 0; j_ < 2; ++j_) dst[j_] = *(const LAS bf16x8*)(kb + ((((2 * ((s0) + j_)) | hh) ^ x15) << 4)); } while (0)
; #define RT_KMM(src, s0) do { _Pragma("unroll") for (int j_ = 0; j_ < 2; ++j_) st = __builtin_amdgcn_mfma_f32_32x32x16_bf16(src[j_], qf[(s0) + j_], st, 0, 0, 0); } while (0)
; __device__ __forceinline__ void p2_ret(const Frame& F, ArgsP a, int layer) {
;     ...
;                 { const LAS unsigned char* kb = lds + RT_K0 + bf * 32768 + (32 * wc + kap) * 512;
;     ...
;                   bf16x8 ka[2], kd[2], kc[2];
;                   RT_KRD(ka, 0); RT_KRD(kd, 2); __builtin_amdgcn_sched_barrier(0);
;                   RT_KRD(kc, 4); RT_KMM(ka, 0); if (pre) { RT_DMA_K(kt + 1, bf ^ 1, 0); RT_DMA_V(kt + 1, bf ^ 1, 0); } __builtin_amdgcn_sched_barrier(0);
;                   RT_KRD(ka, 6); RT_KMM(kd, 2); __builtin_amdgcn_sched_barrier(0);
;                   RT_KRD(kd, 8); RT_KMM(kc, 4); if (pre) { RT_DMA_K(kt + 1, bf ^ 1, 1); RT_DMA_V(kt + 1, bf ^ 1, 1); } __builtin_amdgcn_sched_barrier(0);
;                   RT_KRD(kc, 10); RT_KMM(ka, 6); __builtin_amdgcn_sched_barrier(0);
;                   RT_KRD(ka, 12); RT_KMM(kd, 8); if (pre) { RT_DMA_K(kt + 1, bf ^ 1, 2); RT_DMA_V(kt + 1, bf ^ 1, 2); } __builtin_amdgcn_sched_barrier(0);
;                   RT_KRD(kd, 14); RT_KMM(kc, 10); __builtin_amdgcn_sched_barrier(0);
;                   RT_KMM(ka, 12); if (pre) { RT_DMA_K(kt + 1, bf ^ 1, 3); RT_DMA_V(kt + 1, bf ^ 1, 3); } __builtin_amdgcn_sched_barrier(0);
;                   RT_KMM(kd, 14); __builtin_amdgcn_sched_barrier(0);
.Lrt_sB:
	v_mov_b32_e32 v0, v207
	s_and_b32 s6, s31, 0x8000
	v_lshlrev_b32_e32 v99, 1, v0
	v_lshrrev_b32_e32 v100, 1, v0
	v_and_b32_e32 v98, 19, v0
	v_and_b32_e32 v99, 8, v99
	v_and_b32_e32 v100, 4, v100
	v_or3_b32 v115, v99, v98, v100
	v_ashrrev_i32_e32 v116, 5, v0
	s_add_i32 s4, s6, 0
	v_or_b32_e32 v98, s80, v115
	v_or_b32_e32 v99, 2, v116
	v_lshl_add_u32 v227, v98, 9, s4
	v_bitop3_b32 v98, v115, v116, 15 bitop3:0x6c
	v_bitop3_b32 v99, v115, v99, 15 bitop3:0x6c
	v_lshl_add_u32 v98, v98, 4, v227
	v_lshl_add_u32 v102, v99, 4, v227
	ds_read_b128 v[98:101], v98
	ds_read_b128 v[190:193], v102
	v_or_b32_e32 v102, 4, v116
	v_bitop3_b32 v102, v115, v102, 15 bitop3:0x6c
	v_or_b32_e32 v103, 6, v116
	v_lshl_add_u32 v102, v102, 4, v227
	v_bitop3_b32 v103, v115, v103, 15 bitop3:0x6c
	v_lshl_add_u32 v103, v103, 4, v227
	ds_read_b128 v[194:197], v102
	ds_read_b128 v[198:201], v103
	v_and_b32_e32 v117, 31, v0
	v_add_u32_e32 v216, s23, v116
	v_lshlrev_b32_e32 v217, 12, v216
	v_bitop3_b32 v216, v216, v117, 15 bitop3:0x6c
	v_or_b32_e32 v102, 8, v116
	s_xor_b32 s4, s6, 0x8000
	v_lshl_or_b32 v228, v216, 4, v217
	v_lshrrev_b32_e32 v217, 4, v0
	v_bitop3_b32 v102, v115, v102, 15 bitop3:0x6c
	v_or_b32_e32 v103, 10, v116
	s_add_i32 s5, s22, s4
	v_add_u32_e32 v217, s90, v217
	v_lshl_add_u32 v102, v102, 4, v227
	v_bitop3_b32 v103, v115, v103, 15 bitop3:0x6c
	s_add_i32 s7, s27, 0xfffd0000
	v_lshrrev_b32_e32 v216, 3, v0
	v_xor_b32_e32 v217, v217, v0
	v_lshl_add_u32 v103, v103, 4, v227
	ds_read_b128 v[202:205], v102
	ds_read_b128 v[212:215], v103
	v_add_lshl_u32 v216, v216, s35, 14
	v_lshlrev_b32_e32 v217, 4, v217
	s_movk_i32 s7, 0x70
	v_and_or_b32 v229, v217, s7, v216
	s_add_i32 s7, s25, s30
	s_add_i32 s12, s7, 0x80
	s_mov_b32 s46, s42
	s_mov_b32 s47, s43
	s_waitcnt lgkmcnt(5)
	v_mfma_f32_32x32x16_bf16 v[98:113], v[98:101], v[118:121], 0
	s_waitcnt lgkmcnt(4)
	v_mfma_f32_32x32x16_bf16 v[98:113], v[190:193], v[122:125], v[98:113]
	v_or_b32_e32 v190, 12, v116
	v_or_b32_e32 v191, 14, v116
	v_bitop3_b32 v190, v115, v190, 15 bitop3:0x6c
	v_bitop3_b32 v191, v115, v191, 15 bitop3:0x6c
	v_lshl_add_u32 v190, v190, 4, v227
	v_lshl_add_u32 v216, v191, 4, v227
	ds_read_b128 v[190:193], v190
	ds_read_b128 v[216:219], v216
	s_waitcnt lgkmcnt(5)
	v_mfma_f32_32x32x16_bf16 v[98:113], v[194:197], v[126:129], v[98:113]
	v_or_b32_e32 v194, 16, v116
	v_or_b32_e32 v195, 18, v116
	v_bitop3_b32 v194, v115, v194, 15 bitop3:0x6c
	v_bitop3_b32 v195, v115, v195, 15 bitop3:0x6c
	s_add_i32 s4, s4, 0
	v_lshl_add_u32 v194, v194, 4, v227
	s_waitcnt lgkmcnt(4)
	v_mfma_f32_32x32x16_bf16 v[98:113], v[198:201], v[130:133], v[98:113]
	v_lshl_add_u32 v198, v195, 4, v227
	s_add_i32 s12, s27, 0xfffe0000
	s_add_i32 s4, s4, 0x10000
	ds_read_b128 v[194:197], v194
	ds_read_b128 v[198:201], v198
	s_add_i32 s12, s7, 0x100080
	s_waitcnt lgkmcnt(5)
	v_mfma_f32_32x32x16_bf16 v[98:113], v[202:205], v[134:137], v[98:113]
	s_waitcnt lgkmcnt(4)
	v_mfma_f32_32x32x16_bf16 v[98:113], v[212:215], v[138:141], v[98:113]
	v_or_b32_e32 v202, 20, v116
	v_or_b32_e32 v203, 22, v116
	v_bitop3_b32 v202, v115, v202, 15 bitop3:0x6c
	v_bitop3_b32 v203, v115, v203, 15 bitop3:0x6c
	v_lshl_add_u32 v202, v202, 4, v227
	v_lshl_add_u32 v212, v203, 4, v227
	ds_read_b128 v[202:205], v202
	ds_read_b128 v[212:215], v212
	s_waitcnt lgkmcnt(5)
	v_mfma_f32_32x32x16_bf16 v[98:113], v[190:193], v[142:145], v[98:113]
	v_or_b32_e32 v190, 24, v116
	v_or_b32_e32 v191, 26, v116
	v_bitop3_b32 v190, v115, v190, 15 bitop3:0x6c
	v_bitop3_b32 v191, v115, v191, 15 bitop3:0x6c
	v_lshl_add_u32 v190, v190, 4, v227
	s_add_i32 s12, s27, 0xffff0000
	s_waitcnt lgkmcnt(4)
	v_mfma_f32_32x32x16_bf16 v[98:113], v[216:219], v[146:149], v[98:113]
	v_lshl_add_u32 v216, v191, 4, v227
	ds_read_b128 v[190:193], v190
	ds_read_b128 v[216:219], v216
	s_add_i32 s12, s7, 0x200080
	s_waitcnt lgkmcnt(5)
	v_mfma_f32_32x32x16_bf16 v[98:113], v[194:197], v[150:153], v[98:113]
	s_waitcnt lgkmcnt(4)
	v_mfma_f32_32x32x16_bf16 v[98:113], v[198:201], v[154:157], v[98:113]
	s_waitcnt lgkmcnt(3)
	v_mfma_f32_32x32x16_bf16 v[98:113], v[202:205], v[158:161], v[98:113]
	v_or_b32_e32 v194, 28, v116
	v_or_b32_e32 v195, 30, v116
	v_bitop3_b32 v194, v115, v194, 15 bitop3:0x6c
	v_bitop3_b32 v195, v115, v195, 15 bitop3:0x6c
	v_lshl_add_u32 v194, v194, 4, v227
	v_lshl_add_u32 v198, v195, 4, v227
	ds_read_b128 v[194:197], v194
	ds_read_b128 v[198:201], v198
	s_waitcnt lgkmcnt(4)
	v_mfma_f32_32x32x16_bf16 v[98:113], v[212:215], v[162:165], v[98:113]
	s_add_i32 s7, s7, 0x300080
	s_waitcnt lgkmcnt(3)
	v_mfma_f32_32x32x16_bf16 v[98:113], v[190:193], v[166:169], v[98:113]
	s_waitcnt lgkmcnt(2)
	v_mfma_f32_32x32x16_bf16 v[98:113], v[216:219], v[170:173], v[98:113]
	s_waitcnt lgkmcnt(1)
	v_mfma_f32_32x32x16_bf16 v[98:113], v[194:197], v[174:177], v[98:113]
	s_waitcnt lgkmcnt(0)
	v_mfma_f32_32x32x16_bf16 v[98:113], v[198:201], v[178:181], v[98:113]
	s_branch .Lrt_join
